# static s_setprio 1 for waves 4-7 before the attention loop (asm guide 7.4)
# speedup vs baseline: 1.0058x; 1.0058x over previous
; template<int THRL> __device__ __forceinline__ void attn_unit(int b,int h,int qb,const bf16*Q,const bf16*__restrict__ K,const bf16*__restrict__ V,bf16*O,const float*__restrict__ CK,const float*__restrict__ KMX,const float*__restrict__ QSV,char*shm){
;   int tid_=threadIdx.x; asm volatile("":"+v"(tid_)); const int tid=tid_,lane=tid&63,r32=lane&31,hi=lane>>5; const int wid=__builtin_amdgcn_readfirstlane(tid>>6);
;   const long rowbase=(long)b*SEQ; const int q0=qb*QB;
;   int ts;
;   { const int NT0=(q0+QB)/KVBLK; const float qmx=QSV[0],smn=QSV[1];
;     bool ns0=true,ns1=true;
;     if(lane<NT0){ const float bd=qmx*KMX[lane]-CK[64*lane+63]-smn; ns0=!(bd<-40.f); }
;     if(lane+64<NT0){ const float bd=qmx*KMX[lane+64]-CK[64*(lane+64)+63]-smn; ns1=!(bd<-40.f); }
;     const unsigned long long m0=__ballot(ns0),m1=__ballot(ns1);
;     int first=m0?__builtin_ctzll(m0):(m1?64+__builtin_ctzll(m1):128);
;     first=first<NT0-4?first:NT0-4; ts=__builtin_amdgcn_readfirstlane(first&~1); }
;   CK+=ts*KVBLK;
;   const bf16*Qw=Q+(rowbase+q0+wid*QBLK)*QP+h*D;
;   const bf16*Kh=K+(rowbase+(long)ts*KVBLK)*KP+h*D,*Vh=V+(rowbase+(long)ts*KVBLK)*KP+h*D;
;   const unsigned lds0=(unsigned)(uintptr_t)shm;
;   typedef __attribute__((address_space(3))) const float* lds_fptr; typedef float f32x4v __attribute__((ext_vector_type(4))); const __attribute__((address_space(3))) char* shm3f=(const __attribute__((address_space(3))) char*)shm;
;   float*wsf=(float*)(shm+LDS_WS)+wid*64;
;   const bf16*ksrc=Kh+(long)lane*KP+wid*8;
;   const bf16*vsrc=Vh+(long)(16*(wid&3)+(lane>>2))*KP+(wid>>2)*32+(lane&3)*8;
;   const unsigned kdst=lds0+LDS_K+wid*1024, vdst=lds0+LDS_V+wid*1024;
;     ...
;   const int vb0=(int)(lds0+LDS_V)+((lane>>4)&1)*32+(lane&3)*8+(4*hi+((lane&15)>>2))*64;
;   const char*Kbase=shm+LDS_K; bf16x8 kf[8];
;   const lds_cptr shm3=(lds_cptr)shm; const lds_cptr kp0=shm3+LDS_K+hi*1024+r32*16; const lds_cptr vp0=shm3+LDS_V+((lane>>4)&1)*32+(lane&3)*8+(4*hi+((lane&15)>>2))*64;
;   const int NT=(q0+QB)/KVBLK-ts;
;   { float*ckw=(float*)(shm+LDS_CK); const int nk4=NT*(KVBLK/4);
;     for(int i=tid;i<nk4;i+=NW*64){ const f32x4v c4=*reinterpret_cast<const f32x4v*>(CK+4*i); *reinterpret_cast<f32x4v*>(ckw+4*i)=c4; } }
;   const lds_fptr ckl=(lds_fptr)(shm3f+LDS_CK)+4*hi;
;     ...
;   DMA_K(0,0);DMA_V(0,0);DMA_K(1,SLOTB);
;   bf16x8 qr[4];
;   #pragma unroll
.LBB0_719:
	s_or_b64 exec, exec, s[4:5]
	s_cmp_lt_u32 s70, 0x100
	s_cbranch_scc1 .Lattn_prio_done
	s_setprio 1
.Lattn_prio_done:
	s_lshr_b32 s4, s13, 29
	s_add_i32 s4, s12, s4
	s_ashr_i32 s18, s4, 3
	s_and_b32 s4, s4, 0x3fffff8
	s_ashr_i32 s19, s18, 31
	s_sub_i32 s7, s12, s4
	s_ashr_i32 s13, s70, 6
	s_lshl_b64 s[4:5], s[18:19], 13
	s_ashr_i32 s14, s2, 31
	s_add_u32 s4, s4, s2
	s_addc_u32 s5, s5, s14
	s_lshl_b32 s2, s13, 5
	s_ashr_i32 s14, s2, 31
	s_add_u32 s4, s4, s2
	s_addc_u32 s5, s5, s14
	s_lshl_b64 s[4:5], s[4:5], 11
	s_add_u32 s14, s29, s4
	s_addc_u32 s15, s30, s5
	s_lshl_b32 s4, s7, 6
	s_ashr_i32 s5, s4, 31
	s_lshl_b64 s[16:17], s[4:5], 1
	s_add_u32 s14, s14, s16
	s_addc_u32 s15, s15, s17
	s_ashr_i32 s7, s6, 31
	s_lshl_b64 s[4:5], s[6:7], 15
	s_lshl_b64 s[20:21], s[18:19], 22
	s_add_u32 s4, s4, s20
	s_addc_u32 s5, s5, s21
	s_lshl_b64 s[4:5], s[4:5], 1
	s_add_u32 s20, s31, s4
	s_addc_u32 s21, s34, s5
	s_add_u32 s20, s20, s16
	s_addc_u32 s21, s21, s17
	s_add_u32 s4, s35, s4
	s_addc_u32 s5, s36, s5
	s_add_u32 s4, s4, s16
	v_lshlrev_b32_e32 v192, 10, v218
	s_addc_u32 s5, s5, s17
	v_lshl_add_u64 v[0:1], s[20:21], 0, v[192:193]
	s_lshl_b32 s20, s13, 3
	s_ashr_i32 s21, s20, 31
	s_lshl_b32 s22, s13, 4
	v_lshrrev_b32_e32 v190, 2, v218
	v_lshl_add_u64 v[112:113], s[20:21], 1, v[0:1]
	v_and_or_b32 v0, s22, 48, v190
	v_lshlrev_b32_e32 v0, 10, v0
	v_mov_b32_e32 v1, v193
	v_lshl_add_u64 v[0:1], s[4:5], 0, v[0:1]
	s_ashr_i32 s4, s70, 3
	s_and_b32 s22, s4, 0xffffffe0
	v_lshlrev_b32_e32 v219, 3, v116
	s_ashr_i32 s23, s22, 31
	v_and_b32_e32 v223, 24, v219
	s_lshl_b32 s66, s13, 10
	v_lshl_add_u64 v[0:1], s[22:23], 1, v[0:1]
	v_lshlrev_b32_e32 v2, 1, v223
	v_mov_b32_e32 v3, v193
	s_add_i32 s65, s66, s48
	s_mov_b32 s4, m0
	s_mov_b32 m0, s65
	s_nop 0
	global_load_lds_dwordx4 v[112:113], off
	s_mov_b32 m0, s4
	v_lshl_add_u64 v[114:115], v[0:1], 0, v[2:3]
	s_add_i32 s66, s66, s49
	s_mov_b32 s4, m0
	s_mov_b32 m0, s66
	s_nop 0
	global_load_lds_dwordx4 v[114:115], off
	s_mov_b32 m0, s4
	v_lshrrev_b32_e32 v221, 5, v218
	s_mov_b64 s[4:5], 0x10000
	v_and_b32_e32 v220, 31, v116
	v_lshl_add_u64 v[0:1], v[112:113], 0, s[4:5]
	v_lshlrev_b32_e32 v24, 4, v221
	s_add_i32 s4, s65, 0x2000
	s_mov_b32 s5, m0
	s_mov_b32 m0, s4
	s_nop 0
	global_load_lds_dwordx4 v[0:1], off
	s_mov_b32 m0, s5
	v_lshl_or_b32 v0, v220, 11, v24
	v_mov_b32_e32 v1, v193
	v_lshl_add_u64 v[0:1], s[14:15], 0, v[0:1]
	flat_load_dwordx4 v[108:111], v[0:1]
	flat_load_dwordx4 v[104:107], v[0:1] offset:32
	flat_load_dwordx4 v[100:103], v[0:1] offset:64
	flat_load_dwordx4 v[96:99], v[0:1] offset:96
	v_lshlrev_b32_e32 v0, 10, v221
	v_lshlrev_b32_e32 v1, 4, v220
	v_add3_u32 v230, s28, v0, v1
	s_add_i32 s4, s65, 0x4000
	v_lshl_add_u64 v[0:1], v[112:113], 0, s[46:47]
	s_mov_b32 s5, m0
	s_mov_b32 m0, s4
	s_nop 0
	global_load_lds_dwordx4 v[0:1], off
	s_mov_b32 m0, s5
	s_waitcnt vmcnt(3) lgkmcnt(0)
	s_barrier
	ds_read_b128 v[0:3], v230
	ds_read_b128 v[16:19], v230 offset:512
	v_add_u32_e32 v224, s50, v24
	s_cmp_lt_i32 s64, 5
	v_lshlrev_b32_e32 v222, 2, v221
	v_or_b32_e32 v229, s2, v220
	s_waitcnt vmcnt(0) lgkmcnt(0)
	v_mfma_f32_32x32x16_bf16 v[0:15], v[0:3], v[108:111], 0
	v_mfma_f32_32x32x16_bf16 v[30:45], v[16:19], v[108:111], 0
	ds_read_b128 v[16:19], v230 offset:2048
	ds_read_b128 v[20:23], v230 offset:2560
	s_waitcnt lgkmcnt(1)
	v_mfma_f32_32x32x16_bf16 v[0:15], v[16:19], v[104:107], v[0:15]
	s_waitcnt lgkmcnt(0)
	v_mfma_f32_32x32x16_bf16 v[30:45], v[20:23], v[104:107], v[30:45]
	ds_read_b128 v[16:19], v230 offset:4096
	ds_read_b128 v[20:23], v230 offset:4608
	s_waitcnt lgkmcnt(1)
	v_mfma_f32_32x32x16_bf16 v[0:15], v[16:19], v[100:103], v[0:15]
	s_waitcnt lgkmcnt(0)
	v_mfma_f32_32x32x16_bf16 v[30:45], v[20:23], v[100:103], v[30:45]
	ds_read_b128 v[16:19], v230 offset:6144
	ds_read_b128 v[20:23], v230 offset:6656
	s_waitcnt lgkmcnt(1)
	v_mfma_f32_32x32x16_bf16 v[0:15], v[16:19], v[96:99], v[0:15]
	s_waitcnt lgkmcnt(0)
	v_mfma_f32_32x32x16_bf16 v[30:45], v[20:23], v[96:99], v[30:45]
	s_nop 15
	s_nop 7
	ds_read_b128 v[16:19], v224 offset:96
	ds_read_b128 v[20:23], v224 offset:64
	ds_read_b128 v[24:27], v224
	ds_read_b128 v[46:49], v224 offset:32
	s_waitcnt lgkmcnt(3)
	s_nop 4
	v_sub_f32_e32 v15, v15, v19
	v_sub_f32_e32 v14, v14, v18
	s_waitcnt lgkmcnt(2)
	v_sub_f32_e32 v11, v11, v23
	v_sub_f32_e32 v10, v10, v22
	v_sub_f32_e32 v9, v9, v21
	v_sub_f32_e32 v8, v8, v20
	s_waitcnt lgkmcnt(0)
	v_sub_f32_e32 v7, v7, v49
	v_sub_f32_e32 v6, v6, v48
	v_sub_f32_e32 v5, v5, v47
	v_sub_f32_e32 v4, v4, v46
	v_sub_f32_e32 v3, v3, v27
	v_sub_f32_e32 v2, v2, v26
	v_sub_f32_e32 v1, v1, v25
	v_sub_f32_e32 v0, v0, v24
	ds_read_b128 v[18:21], v224 offset:224
	ds_read_b128 v[22:25], v224 offset:192
	ds_read_b128 v[46:49], v224 offset:128
	ds_read_b128 v[26:29], v224 offset:160
	v_sub_f32_e32 v13, v13, v17
	v_sub_f32_e32 v12, v12, v16
	s_waitcnt lgkmcnt(3)
	v_sub_f32_e32 v17, v45, v21
	v_sub_f32_e32 v16, v44, v20
	v_sub_f32_e32 v19, v43, v19
	v_sub_f32_e32 v18, v42, v18
	s_waitcnt lgkmcnt(2)
	v_sub_f32_e32 v21, v41, v25
	v_sub_f32_e32 v20, v40, v24
	v_sub_f32_e32 v23, v39, v23
	v_sub_f32_e32 v22, v38, v22
	s_waitcnt lgkmcnt(0)
	v_sub_f32_e32 v25, v37, v29
	v_sub_f32_e32 v24, v36, v28
	v_sub_f32_e32 v27, v35, v27
	v_sub_f32_e32 v26, v34, v26
	v_sub_f32_e32 v29, v33, v49
	v_sub_f32_e32 v28, v32, v48
	v_sub_f32_e32 v31, v31, v47
	v_sub_f32_e32 v30, v30, v46
	s_cbranch_scc0 .LBB0_721
; __device__ __forceinline__ void cmask(f32x16&p0,f32x16&p1,int jb,int qrel,int hi){
;   const float NEG=-INFINITY; int kb=64*jb+4*hi;
;   #pragma unroll
;   for(int r=0;r<16;++r){int kv=kb+(r&3)+8*(r>>2); if(kv>qrel)p0[r]=NEG; if(kv+32>qrel)p1[r]=NEG;}
; }
	s_lshl_b32 s2, s64, 6
	v_subrev_u32_e32 v32, s2, v222
	v_add_u32_e32 v34, 0x120, v32
	v_add_u32_e32 v33, 0x100, v32
	v_cmp_le_i32_e64 s[4:5], v34, v229
	v_cmp_le_i32_e32 vcc, v33, v229
	s_nop 0
	v_cndmask_b32_e64 v30, v217, v30, s[4:5]
	v_cmp_lt_i32_e64 s[4:5], v33, v229
	v_add_u32_e32 v33, 0x121, v32
	v_cndmask_b32_e32 v0, v217, v0, vcc
	v_cmp_le_i32_e32 vcc, v33, v229
	v_add_u32_e32 v33, 0x102, v32
	v_cndmask_b32_e64 v1, v217, v1, s[4:5]
	v_cndmask_b32_e32 v31, v217, v31, vcc
	v_cmp_le_i32_e32 vcc, v33, v229
	v_add_u32_e32 v33, 0x122, v32
	s_nop 0
	v_cndmask_b32_e32 v2, v217, v2, vcc
	v_cmp_le_i32_e32 vcc, v33, v229
	v_add_u32_e32 v33, 0x103, v32
	s_nop 0
	v_cndmask_b32_e32 v28, v217, v28, vcc
	v_cmp_le_i32_e32 vcc, v33, v229
	v_add_u32_e32 v33, 0x123, v32
	s_nop 0
	v_cndmask_b32_e32 v3, v217, v3, vcc
	v_cmp_le_i32_e32 vcc, v33, v229
	v_add_u32_e32 v33, 0x108, v32
	s_nop 0
	v_cndmask_b32_e32 v29, v217, v29, vcc
	v_cmp_le_i32_e32 vcc, v33, v229
	v_add_u32_e32 v33, 0x128, v32
	s_nop 0
	v_cndmask_b32_e32 v4, v217, v4, vcc
	v_cmp_le_i32_e32 vcc, v33, v229
	v_add_u32_e32 v33, 0x109, v32
	s_nop 0
	v_cndmask_b32_e32 v26, v217, v26, vcc
	v_cmp_le_i32_e32 vcc, v33, v229
	v_add_u32_e32 v33, 0x129, v32
	s_nop 0
	v_cndmask_b32_e32 v5, v217, v5, vcc
	v_cmp_le_i32_e32 vcc, v33, v229
	v_add_u32_e32 v33, 0x10a, v32
	s_nop 0
	v_cndmask_b32_e32 v27, v217, v27, vcc
	v_cmp_le_i32_e32 vcc, v33, v229
	v_add_u32_e32 v33, 0x12a, v32
	s_nop 0
	v_cndmask_b32_e32 v6, v217, v6, vcc
	v_cmp_le_i32_e32 vcc, v33, v229
	v_add_u32_e32 v33, 0x10b, v32
	s_nop 0
	v_cndmask_b32_e32 v24, v217, v24, vcc
	v_cmp_le_i32_e32 vcc, v33, v229
	v_add_u32_e32 v33, 0x12b, v32
	s_nop 0
	v_cndmask_b32_e32 v7, v217, v7, vcc
	v_cmp_le_i32_e32 vcc, v33, v229
	v_add_u32_e32 v33, 0x110, v32
	s_nop 0
	v_cndmask_b32_e32 v25, v217, v25, vcc
	v_cmp_le_i32_e32 vcc, v33, v229
	v_add_u32_e32 v33, 0x130, v32
	s_nop 0
	v_cndmask_b32_e32 v8, v217, v8, vcc
	v_cmp_le_i32_e32 vcc, v33, v229
	v_add_u32_e32 v33, 0x111, v32
	s_nop 0
	v_cndmask_b32_e32 v22, v217, v22, vcc
	v_cmp_le_i32_e32 vcc, v33, v229
	v_add_u32_e32 v33, 0x131, v32
	s_nop 0
	v_cndmask_b32_e32 v9, v217, v9, vcc
	v_cmp_le_i32_e32 vcc, v33, v229
	v_add_u32_e32 v33, 0x112, v32
	s_nop 0
	v_cndmask_b32_e32 v23, v217, v23, vcc
	v_cmp_le_i32_e32 vcc, v33, v229
	v_add_u32_e32 v33, 0x132, v32
	s_nop 0
	v_cndmask_b32_e32 v10, v217, v10, vcc
	v_cmp_le_i32_e32 vcc, v33, v229
	v_add_u32_e32 v33, 0x113, v32
	s_nop 0
	v_cndmask_b32_e32 v20, v217, v20, vcc
	v_cmp_le_i32_e32 vcc, v33, v229
	v_add_u32_e32 v33, 0x133, v32
	s_nop 0
	v_cndmask_b32_e32 v11, v217, v11, vcc
	v_cmp_le_i32_e32 vcc, v33, v229
	v_add_u32_e32 v33, 0x118, v32
	s_nop 0
	v_cndmask_b32_e32 v21, v217, v21, vcc
	v_cmp_le_i32_e32 vcc, v33, v229
	v_add_u32_e32 v33, 0x138, v32
	s_nop 0
	v_cndmask_b32_e32 v12, v217, v12, vcc
	v_cmp_le_i32_e32 vcc, v33, v229
	v_add_u32_e32 v33, 0x119, v32
	s_nop 0
	v_cndmask_b32_e32 v18, v217, v18, vcc
	v_cmp_le_i32_e32 vcc, v33, v229
	v_add_u32_e32 v33, 0x139, v32
	s_nop 0
	v_cndmask_b32_e32 v13, v217, v13, vcc
	v_cmp_le_i32_e32 vcc, v33, v229
	v_add_u32_e32 v33, 0x11a, v32
	s_nop 0
	v_cndmask_b32_e32 v19, v217, v19, vcc
	v_cmp_le_i32_e32 vcc, v33, v229
	v_add_u32_e32 v33, 0x13a, v32
	s_nop 0
	v_cndmask_b32_e32 v14, v217, v14, vcc
	v_cmp_le_i32_e32 vcc, v33, v229
	v_add_u32_e32 v33, 0x11b, v32
	v_add_u32_e32 v32, 0x13b, v32
	v_cndmask_b32_e32 v16, v217, v16, vcc
	v_cmp_le_i32_e32 vcc, v33, v229
	s_nop 1
	v_cndmask_b32_e32 v15, v217, v15, vcc
	v_cmp_le_i32_e32 vcc, v32, v229
	s_nop 1
	v_cndmask_b32_e32 v17, v217, v17, vcc
